# baseline (speedup 1.0000x reference)
; #define SBAR() __builtin_amdgcn_sched_barrier(0)
; #define K8LD(RP, I, SW) __builtin_shufflevector(*(const i32x4*)((RP) + (((4 * (I) + 2 * hi) ^ (SW)) * 16)), *(const i32x4*)((RP) + ((((4 * (I) + 2 * hi) ^ (SW)) * 16) ^ 16)), 0, 1, 2, 3, 4, 5, 6, 7)
; #define SWAIT() do { if constexpr (FIXED) asm volatile("s_waitcnt vmcnt(2)" ::: "memory"); else if constexpr (SD == 2) asm volatile("s_waitcnt vmcnt(4)" ::: "memory"); else asm volatile("s_waitcnt vmcnt(0)" ::: "memory"); } while (0)
; #define FSM(P0, P1, AL) do { if constexpr (FIXED) finishSM8(P0, P1, l_reg, pa8); else finishSM(P0, P1, AL, l_reg, pa0, pa1, pa2, pa3); } while (0)
; #define PVX(VOFF, PE) do { if constexpr (FIXED) pv8<true>(o, (const char*)V_lds + (VOFF), pa8, r32, hi, PE); else pv_d0(o, vb0 + (VOFF), pa0, pa1, pa2, pa3); } while (0)
; __device__ __forceinline__ void qkt8(f32x16& p0, f32x16& p1, const char* Ks, const i32x8* q8, int r32, int hi) {
;     const int s127 = 127, s124 = 124;
;     const int sw0 = (r32 >> 1) & 7, sw1 = ((32 + r32) >> 1) & 7; const char* rp0 = Ks + r32 * 128; const char* rp1 = Ks + (32 + r32) * 128;
;     ...
;     {   i32x8 ka = K8LD(rp0, 0, sw0), kb = K8LD(rp1, 0, sw1);
;         asm volatile("s_waitcnt lgkmcnt(0)" ::: "memory");
;         asm volatile("v_mfma_scale_f32_32x32x64_f8f6f4 %0, %1, %2, -4.0, %3, %4 op_sel_hi:[0,0,0]" : "=&v"(p0) : "v"(ka), "v"(q8[0]), "v"(s127), "v"(s124));
;         asm volatile("v_mfma_scale_f32_32x32x64_f8f6f4 %0, %1, %2, -4.0, %3, %4 op_sel_hi:[0,0,0]" : "=&v"(p1) : "v"(kb), "v"(q8[0]), "v"(s127), "v"(s124)); }
;     {   i32x8 ka = K8LD(rp0, 1, sw0), kb = K8LD(rp1, 1, sw1);
;         asm volatile("s_waitcnt lgkmcnt(0)" ::: "memory");
;         asm volatile("v_mfma_scale_f32_32x32x64_f8f6f4 %0, %1, %2, %0, %3, %4 op_sel_hi:[0,0,0]" : "+v"(p0) : "v"(ka), "v"(q8[1]), "v"(s127), "v"(s124));
;         asm volatile("v_mfma_scale_f32_32x32x64_f8f6f4 %0, %1, %2, %0, %3, %4 op_sel_hi:[0,0,0]" : "+v"(p1) : "v"(kb), "v"(q8[1]), "v"(s127), "v"(s124)); }
; }
; template <bool FIXED> ...
;     ...
;     for (int j = 1; j + 1 < NT; j += 2) {
;         SBAR(); QKT(pB0, pB1, (const char*)K_lds + bc * SHM_K);
;         FSM(pA0, pA1, alA); SBAR();
;         SLOAD(SO, (j + SD) * KVBLK); SBAR();
;         PVX(bp * (int)SHM_V, pB0); PSMG(pB0, pB1, mnB, alB);
;         SWAIT(); SWRITE(bn, SE);
;         RESCX(alB); __syncthreads();
.Lf4_loop:
	s_mov_b32 s47, s35
	s_mov_b32 s35, s44
	s_lshl_b32 s49, s47, 14
	s_lshl_b32 s50, s44, 14
	v_add_u32_e32 v250, v252, v202
	v_add_u32_e32 v251, v252, v203
	v_add_u32_e32 v253, s50, v207
	ds_read_b128 v[216:219], v250 offset:53248
	ds_read_b128 v[220:223], v251 offset:53248
	ds_read_b128 v[136:139], v253
	ds_read_b128 v[140:143], v253 offset:16
	ds_read_b128 v[240:243], v253 offset:2560
	ds_read_b128 v[244:247], v253 offset:2576
	s_waitcnt lgkmcnt(6)
	v_mfma_scale_f32_32x32x64_f8f6f4 v[96:111], v[208:215], v[152:159], -4.0, v189, v190 op_sel_hi:[0,0,0]
	v_cvt_pk_bf8_f32 v128, v64, v65
	v_cvt_pk_bf8_f32 v129, v68, v69
	ds_read_b128 v[208:211], v253 offset:5120
	ds_read_b128 v[212:215], v253 offset:5136
	v_cvt_pk_bf8_f32 v130, v72, v73
	v_cvt_pk_bf8_f32 v131, v76, v77
	v_exp_f32_e32 v80, v80
	v_exp_f32_e32 v81, v81
	v_exp_f32_e32 v84, v84
	v_exp_f32_e32 v85, v85
	s_waitcnt lgkmcnt(6)
	v_mfma_scale_f32_32x32x64_f8f6f4 v[112:127], v[216:223], v[152:159], -4.0, v189, v190 op_sel_hi:[0,0,0]
	v_cvt_pk_bf8_f32 v128, v66, v67 op_sel:[0,0,1]
	v_cvt_pk_bf8_f32 v129, v70, v71 op_sel:[0,0,1]
	ds_read_b128 v[216:219], v253 offset:7680
	ds_read_b128 v[220:223], v253 offset:7696
	v_cvt_pk_bf8_f32 v130, v74, v75 op_sel:[0,0,1]
	v_cvt_pk_bf8_f32 v131, v78, v79 op_sel:[0,0,1]
	v_exp_f32_e32 v88, v88
	v_exp_f32_e32 v89, v89
	v_exp_f32_e32 v92, v92
	v_exp_f32_e32 v93, v93
	v_mfma_scale_f32_32x32x64_f8f6f4 v[96:111], v[224:231], v[144:151], v[96:111], v189, v190 op_sel_hi:[0,0,0]
	v_exp_f32_e32 v82, v82
	v_exp_f32_e32 v83, v83
	v_exp_f32_e32 v86, v86
	v_exp_f32_e32 v87, v87
	v_exp_f32_e32 v90, v90
	v_exp_f32_e32 v91, v91
	v_exp_f32_e32 v94, v94
	v_exp_f32_e32 v95, v95
	v_cvt_pk_bf8_f32 v132, v80, v81
	v_cvt_pk_bf8_f32 v133, v84, v85
	v_mfma_scale_f32_32x32x64_f8f6f4 v[112:127], v[232:239], v[144:151], v[112:127], v189, v190 op_sel_hi:[0,0,0]
	v_cvt_pk_bf8_f32 v134, v88, v89
	v_cvt_pk_bf8_f32 v135, v92, v93
	v_cvt_pk_bf8_f32 v132, v82, v83 op_sel:[0,0,1]
	v_cvt_pk_bf8_f32 v133, v86, v87 op_sel:[0,0,1]
	v_cvt_pk_bf8_f32 v134, v90, v91 op_sel:[0,0,1]
	v_cvt_pk_bf8_f32 v135, v94, v95 op_sel:[0,0,1]
	v_lshl_add_u64 v[186:187], s[28:29], 0, v[182:183]
	v_add_co_u32_e32 v250, vcc, s62, v186
	v_lshl_add_u64 v[184:185], s[28:29], 0, v[180:181]
	v_add_f32_e32 v248, v64, v65
	v_addc_co_u32_e32 v251, vcc, 0, v187, vcc
	v_add_co_u32_e32 v252, vcc, s63, v184
	v_add_f32_e32 v249, v80, v81
	v_add_f32_e32 v248, v66, v248
	v_addc_co_u32_e32 v253, vcc, 0, v185, vcc
	global_load_dwordx4 v[172:175], v[250:251], off
	global_load_dwordx4 v[168:171], v[252:253], off
	v_add_f32_e32 v249, v82, v249
	s_waitcnt lgkmcnt(6)
	v_mfma_f32_32x32x64_f8f6f4 v[0:15], v[128:135], v[136:143], v[0:15] cbsz:1
	s_lshl_b32 s44, s46, 14
	v_add_u32_e32 v250, s44, v199
	s_add_i32 s48, s44, 0
	v_add_u32_e32 v251, s48, v198
	v_add_u32_e32 v252, s48, v200
	s_waitcnt vmcnt(2)
	ds_write_b128 v250, v[164:167]
	ds_write_b64 v251, v[160:161] offset:49152
	ds_write_b64 v252, v[162:163] offset:49152
	v_add_f32_e32 v248, v67, v248
	v_add_f32_e32 v249, v83, v249
	v_add_f32_e32 v248, v68, v248
	v_add_f32_e32 v249, v84, v249
	v_add_f32_e32 v248, v69, v248
	v_add_f32_e32 v249, v85, v249
	v_add_f32_e32 v248, v70, v248
	v_add_f32_e32 v249, v86, v249
	v_add_f32_e32 v248, v71, v248
	v_add_f32_e32 v249, v87, v249
	v_add_f32_e32 v248, v72, v248
	v_add_f32_e32 v249, v88, v249
	s_waitcnt lgkmcnt(7)
	v_mfma_f32_32x32x64_f8f6f4 v[16:31], v[128:135], v[240:247], v[16:31] cbsz:1
	v_add_f32_e32 v248, v73, v248
	v_add_f32_e32 v249, v89, v249
	v_add_f32_e32 v248, v74, v248
	v_add_f32_e32 v249, v90, v249
	v_add_f32_e32 v248, v75, v248
	v_add_f32_e32 v249, v91, v249
	v_add_f32_e32 v248, v76, v248
	v_add_f32_e32 v249, v92, v249
	v_add_f32_e32 v248, v77, v248
	v_add_f32_e32 v249, v93, v249
	v_exp_f32_e32 v96, v96
	v_exp_f32_e32 v97, v97
	v_exp_f32_e32 v98, v98
	v_exp_f32_e32 v99, v99
	s_waitcnt lgkmcnt(0)
	s_barrier
; #define SBAR() __builtin_amdgcn_sched_barrier(0)
; #define K8LD(RP, I, SW) __builtin_shufflevector(*(const i32x4*)((RP) + (((4 * (I) + 2 * hi) ^ (SW)) * 16)), *(const i32x4*)((RP) + ((((4 * (I) + 2 * hi) ^ (SW)) * 16) ^ 16)), 0, 1, 2, 3, 4, 5, 6, 7)
; #define SWAIT() do { if constexpr (FIXED) asm volatile("s_waitcnt vmcnt(2)" ::: "memory"); else if constexpr (SD == 2) asm volatile("s_waitcnt vmcnt(4)" ::: "memory"); else asm volatile("s_waitcnt vmcnt(0)" ::: "memory"); } while (0)
; #define FSM(P0, P1, AL) do { if constexpr (FIXED) finishSM8(P0, P1, l_reg, pa8); else finishSM(P0, P1, AL, l_reg, pa0, pa1, pa2, pa3); } while (0)
; #define PSMG(P0, P1, MN, AL) do { if constexpr (!FIXED) partialSM(P0, P1, m_reg, MN, AL); } while (0)
; __device__ __forceinline__ void qkt8(f32x16& p0, f32x16& p1, const char* Ks, const i32x8* q8, int r32, int hi) {
;     const int s127 = 127, s124 = 124;
;     const int sw0 = (r32 >> 1) & 7, sw1 = ((32 + r32) >> 1) & 7; const char* rp0 = Ks + r32 * 128; const char* rp1 = Ks + (32 + r32) * 128;
;     ...
;     {   i32x8 ka = K8LD(rp0, 0, sw0), kb = K8LD(rp1, 0, sw1);
;         asm volatile("s_waitcnt lgkmcnt(0)" ::: "memory");
;         asm volatile("v_mfma_scale_f32_32x32x64_f8f6f4 %0, %1, %2, -4.0, %3, %4 op_sel_hi:[0,0,0]" : "=&v"(p0) : "v"(ka), "v"(q8[0]), "v"(s127), "v"(s124));
;         asm volatile("v_mfma_scale_f32_32x32x64_f8f6f4 %0, %1, %2, -4.0, %3, %4 op_sel_hi:[0,0,0]" : "=&v"(p1) : "v"(kb), "v"(q8[0]), "v"(s127), "v"(s124)); }
;     {   i32x8 ka = K8LD(rp0, 1, sw0), kb = K8LD(rp1, 1, sw1);
;         asm volatile("s_waitcnt lgkmcnt(0)" ::: "memory");
;         asm volatile("v_mfma_scale_f32_32x32x64_f8f6f4 %0, %1, %2, %0, %3, %4 op_sel_hi:[0,0,0]" : "+v"(p0) : "v"(ka), "v"(q8[1]), "v"(s127), "v"(s124));
;         asm volatile("v_mfma_scale_f32_32x32x64_f8f6f4 %0, %1, %2, %0, %3, %4 op_sel_hi:[0,0,0]" : "+v"(p1) : "v"(kb), "v"(q8[1]), "v"(s127), "v"(s124)); }
; }
; template <bool FIXED> ...
;     ...
;         SBAR(); QKT(pA0, pA1, (const char*)K_lds + bc * SHM_K);
;         FSM(pB0, pB1, alB); SBAR();
;         if (SD == 1 || j + 3 < NT) SLOAD(SE, (j + 1 + SD) * KVBLK); SBAR();
;         PVX(bp * (int)SHM_V, pA0); PSMG(pA0, pA1, mnA, alA);
;         SWAIT(); SWRITE(bn, SO);
;         RESCX(alA); __syncthreads();
;         { const int t_ = bp; bp = bc; bc = bn; bn = t_; }
;     }
	v_add_u32_e32 v252, s48, v201
	v_add_u32_e32 v250, v252, v205
	v_add_u32_e32 v251, v252, v206
	ds_read_b128 v[224:227], v250 offset:49152
	ds_read_b128 v[228:231], v251 offset:49152
	ds_read_b128 v[232:235], v250 offset:53248
	ds_read_b128 v[236:239], v251 offset:53248
	v_mfma_f32_32x32x64_f8f6f4 v[32:47], v[128:135], v[208:215], v[32:47] cbsz:1
	v_add_u32_e32 v250, v252, v202
	v_add_u32_e32 v251, v252, v203
	v_add_f32_e32 v248, v78, v248
	v_add_f32_e32 v249, v94, v249
	ds_read_b128 v[208:211], v250 offset:49152
	ds_read_b128 v[212:215], v251 offset:49152
	v_exp_f32_e32 v100, v100
	v_exp_f32_e32 v101, v101
	v_exp_f32_e32 v102, v102
	v_exp_f32_e32 v103, v103
	v_exp_f32_e32 v104, v104
	v_exp_f32_e32 v105, v105
	v_mfma_f32_32x32x64_f8f6f4 v[48:63], v[128:135], v[216:223], v[48:63] cbsz:1
	v_add_f32_e32 v248, v79, v248
	v_add_f32_e32 v249, v95, v249
	v_add_f32_e32 v178, v178, v248
	v_add_f32_e32 v178, v178, v249
	v_exp_f32_e32 v106, v106
	v_exp_f32_e32 v107, v107
	v_exp_f32_e32 v108, v108
	v_exp_f32_e32 v109, v109
	v_exp_f32_e32 v110, v110
	v_exp_f32_e32 v111, v111
	v_add_u32_e32 v250, v252, v202
	v_add_u32_e32 v251, v252, v203
	v_add_u32_e32 v253, s49, v207
	s_add_i32 s49, s50, 0
	ds_read_b128 v[216:219], v250 offset:53248
	ds_read_b128 v[220:223], v251 offset:53248
	ds_read_b128 v[136:139], v253
	ds_read_b128 v[140:143], v253 offset:16
	ds_read_b128 v[240:243], v253 offset:2560
	ds_read_b128 v[244:247], v253 offset:2576
	s_waitcnt lgkmcnt(6)
	v_mfma_scale_f32_32x32x64_f8f6f4 v[64:79], v[208:215], v[152:159], -4.0, v189, v190 op_sel_hi:[0,0,0]
	v_cvt_pk_bf8_f32 v128, v96, v97
	v_cvt_pk_bf8_f32 v129, v100, v101
	ds_read_b128 v[208:211], v253 offset:5120
	ds_read_b128 v[212:215], v253 offset:5136
	v_cvt_pk_bf8_f32 v130, v104, v105
	v_cvt_pk_bf8_f32 v131, v108, v109
	v_exp_f32_e32 v112, v112
	v_exp_f32_e32 v113, v113
	v_exp_f32_e32 v116, v116
	v_exp_f32_e32 v117, v117
	s_waitcnt lgkmcnt(6)
	v_mfma_scale_f32_32x32x64_f8f6f4 v[80:95], v[216:223], v[152:159], -4.0, v189, v190 op_sel_hi:[0,0,0]
	v_cvt_pk_bf8_f32 v128, v98, v99 op_sel:[0,0,1]
	v_cvt_pk_bf8_f32 v129, v102, v103 op_sel:[0,0,1]
	ds_read_b128 v[216:219], v253 offset:7680
	ds_read_b128 v[220:223], v253 offset:7696
	v_cvt_pk_bf8_f32 v130, v106, v107 op_sel:[0,0,1]
	v_cvt_pk_bf8_f32 v131, v110, v111 op_sel:[0,0,1]
	v_exp_f32_e32 v120, v120
	v_exp_f32_e32 v121, v121
	v_exp_f32_e32 v124, v124
	v_exp_f32_e32 v125, v125
	v_mfma_scale_f32_32x32x64_f8f6f4 v[64:79], v[224:231], v[144:151], v[64:79], v189, v190 op_sel_hi:[0,0,0]
	v_exp_f32_e32 v114, v114
	v_exp_f32_e32 v115, v115
	v_exp_f32_e32 v118, v118
	v_exp_f32_e32 v119, v119
	v_exp_f32_e32 v122, v122
	v_exp_f32_e32 v123, v123
	v_exp_f32_e32 v126, v126
	v_exp_f32_e32 v127, v127
	v_cvt_pk_bf8_f32 v132, v112, v113
	v_cvt_pk_bf8_f32 v133, v116, v117
	v_mfma_scale_f32_32x32x64_f8f6f4 v[80:95], v[232:239], v[144:151], v[80:95], v189, v190 op_sel_hi:[0,0,0]
	v_cvt_pk_bf8_f32 v134, v120, v121
	v_cvt_pk_bf8_f32 v135, v124, v125
	v_cvt_pk_bf8_f32 v132, v114, v115 op_sel:[0,0,1]
	v_cvt_pk_bf8_f32 v133, v118, v119 op_sel:[0,0,1]
	v_cvt_pk_bf8_f32 v134, v122, v123 op_sel:[0,0,1]
	v_cvt_pk_bf8_f32 v135, v126, v127 op_sel:[0,0,1]
	s_cmp_ge_u32 s3, s69
	s_cselect_b64 s[44:45], -1, 0
	s_and_b64 vcc, exec, s[44:45]
	s_cbranch_vccnz .Lf4_skip
	v_add_co_u32_e32 v160, vcc, 0x49730000, v186
	v_add_f32_e32 v248, v96, v97
	v_add_f32_e32 v249, v112, v113
	v_addc_co_u32_e32 v161, vcc, 0, v187, vcc
	v_add_co_u32_e32 v162, vcc, 0x48b30000, v184
	v_add_f32_e32 v248, v98, v248
	v_add_f32_e32 v249, v114, v249
	v_addc_co_u32_e32 v163, vcc, 0, v185, vcc
	global_load_dwordx4 v[164:167], v[160:161], off
	s_nop 0
	global_load_dwordx4 v[160:163], v[162:163], off
	s_branch .Lf4_sedone
